# v4 + early post-MFMA barrier arrival per GEMM: P1 5, P4 4, P6 4, P7 3 MFMAs, trailing at prio 2
# speedup vs baseline: 1.0166x; 1.0007x over previous
.LBB0_229:
	ds_read_b128 v[144:147], v149
	ds_read_b128 v[154:157], v149 offset:1024
	ds_read_b128 v[158:161], v149 offset:2048
	ds_read_b128 v[162:165], v149 offset:3072
	ds_read_b128 v[166:169], v150
	ds_read_b128 v[170:173], v150 offset:1024
	ds_read_b128 v[174:177], v150 offset:2048
	ds_read_b128 v[178:181], v150 offset:3072
	s_add_u32 s30, s28, 0xfff00080
	s_addc_u32 s31, s29, -1
	s_cmp_eq_u32 s67, 60
	s_cselect_b32 s37, s21, s31
	s_cselect_b32 s36, s59, s30
	s_cselect_b32 s31, s19, s62
	s_cselect_b32 s30, s60, s61
	v_lshl_add_u64 v[214:215], s[28:29], 0, v[136:137]
	s_add_i32 m0, s27, 0xc000
	ds_read_b128 v[182:185], v151
	ds_read_b128 v[186:189], v151 offset:1024
	ds_read_b128 v[190:193], v151 offset:2048
	ds_read_b128 v[194:197], v151 offset:3072
	ds_read_b128 v[198:201], v151 offset:4096
	ds_read_b128 v[202:205], v151 offset:5120
	ds_read_b128 v[206:209], v151 offset:6144
	ds_read_b128 v[210:213], v151 offset:7168
	global_load_lds_dwordx4 v[214:215], off
	v_lshl_add_u64 v[214:215], s[28:29], 0, v[138:139]
	s_add_i32 m0, s27, 0xe000
	s_nop 0
	global_load_lds_dwordx4 v[214:215], off
	s_waitcnt vmcnt(8)
	s_waitcnt lgkmcnt(0)
	s_barrier
	s_setprio 1
	s_waitcnt lgkmcnt(0)
	v_mfma_f32_16x16x32_bf16 v[124:127], v[144:147], v[182:185], v[124:127]
	v_mfma_f32_16x16x32_bf16 v[120:123], v[158:161], v[182:185], v[120:123]
	v_mfma_f32_16x16x32_bf16 v[112:115], v[144:147], v[190:193], v[112:115]
	v_mfma_f32_16x16x32_bf16 v[104:107], v[158:161], v[190:193], v[104:107]
	v_mfma_f32_16x16x32_bf16 v[96:99], v[144:147], v[198:201], v[96:99]
	v_mfma_f32_16x16x32_bf16 v[88:91], v[158:161], v[198:201], v[88:91]
	v_mfma_f32_16x16x32_bf16 v[80:83], v[144:147], v[206:209], v[80:83]
	v_mfma_f32_16x16x32_bf16 v[72:75], v[158:161], v[206:209], v[72:75]
	v_mfma_f32_16x16x32_bf16 v[124:127], v[154:157], v[186:189], v[124:127]
	v_mfma_f32_16x16x32_bf16 v[120:123], v[162:165], v[186:189], v[120:123]
	v_mfma_f32_16x16x32_bf16 v[112:115], v[154:157], v[194:197], v[112:115]
	v_mfma_f32_16x16x32_bf16 v[104:107], v[162:165], v[194:197], v[104:107]
	v_mfma_f32_16x16x32_bf16 v[96:99], v[154:157], v[202:205], v[96:99]
	v_mfma_f32_16x16x32_bf16 v[88:91], v[162:165], v[202:205], v[88:91]
	v_mfma_f32_16x16x32_bf16 v[80:83], v[154:157], v[210:213], v[80:83]
	v_mfma_f32_16x16x32_bf16 v[72:75], v[162:165], v[210:213], v[72:75]
	s_setprio 0
	s_setprio 1
	v_mfma_f32_16x16x32_bf16 v[116:119], v[166:169], v[182:185], v[116:119]
	v_mfma_f32_16x16x32_bf16 v[108:111], v[174:177], v[182:185], v[108:111]
	v_mfma_f32_16x16x32_bf16 v[100:103], v[166:169], v[190:193], v[100:103]
	v_mfma_f32_16x16x32_bf16 v[92:95], v[174:177], v[190:193], v[92:95]
	v_mfma_f32_16x16x32_bf16 v[84:87], v[166:169], v[198:201], v[84:87]
	v_mfma_f32_16x16x32_bf16 v[76:79], v[174:177], v[198:201], v[76:79]
	v_mfma_f32_16x16x32_bf16 v[68:71], v[166:169], v[206:209], v[68:71]
	v_mfma_f32_16x16x32_bf16 v[64:67], v[174:177], v[206:209], v[64:67]
	v_mfma_f32_16x16x32_bf16 v[116:119], v[170:173], v[186:189], v[116:119]
	v_mfma_f32_16x16x32_bf16 v[108:111], v[178:181], v[186:189], v[108:111]
	s_setprio 2
	s_barrier
	v_mfma_f32_16x16x32_bf16 v[100:103], v[170:173], v[194:197], v[100:103]
	v_mfma_f32_16x16x32_bf16 v[92:95], v[178:181], v[194:197], v[92:95]
	v_mfma_f32_16x16x32_bf16 v[84:87], v[170:173], v[202:205], v[84:87]
	v_mfma_f32_16x16x32_bf16 v[76:79], v[178:181], v[202:205], v[76:79]
	v_mfma_f32_16x16x32_bf16 v[68:71], v[170:173], v[210:213], v[68:71]
	v_mfma_f32_16x16x32_bf16 v[64:67], v[178:181], v[210:213], v[64:67]
	s_setprio 0
	s_add_i32 s68, s56, s46
	v_lshl_add_u64 v[214:215], s[30:31], 0, v[130:131]
	s_mov_b32 m0, s68
	ds_read_b128 v[182:185], v151 offset:16384
	ds_read_b128 v[186:189], v151 offset:17408
	ds_read_b128 v[190:193], v151 offset:18432
	ds_read_b128 v[194:197], v151 offset:19456
	ds_read_b128 v[198:201], v151 offset:20480
	ds_read_b128 v[202:205], v151 offset:21504
	ds_read_b128 v[206:209], v151 offset:22528
	ds_read_b128 v[210:213], v151 offset:23552
	global_load_lds_dwordx4 v[214:215], off
	s_add_i32 m0, s68, 0x2000
	s_add_u32 s68, s30, 0x100000
	v_lshl_add_u64 v[216:217], s[30:31], 0, v[134:135]
	s_addc_u32 s69, s31, 0
	s_add_i32 s70, s57, s46
	global_load_lds_dwordx4 v[216:217], off
	v_lshl_add_u64 v[218:219], s[68:69], 0, v[130:131]
	s_mov_b32 m0, s70
	v_lshl_add_u64 v[220:221], s[36:37], 0, v[132:133]
	global_load_lds_dwordx4 v[218:219], off
	v_lshl_add_u64 v[218:219], s[68:69], 0, v[134:135]
	s_add_i32 m0, s70, 0x2000
	s_nop 0
	global_load_lds_dwordx4 v[218:219], off
	v_lshl_add_u64 v[218:219], s[36:37], 0, v[128:129]
	s_mov_b32 m0, s27
	s_nop 0
	global_load_lds_dwordx4 v[218:219], off
	s_mov_b32 m0, s47
	s_nop 0
	global_load_lds_dwordx4 v[220:221], off
	s_waitcnt vmcnt(8)
	s_waitcnt lgkmcnt(0)
	s_barrier
	s_setprio 1
	s_waitcnt lgkmcnt(0)
	v_mfma_f32_16x16x32_bf16 v[60:63], v[144:147], v[182:185], v[60:63]
	v_mfma_f32_16x16x32_bf16 v[56:59], v[158:161], v[182:185], v[56:59]
	v_mfma_f32_16x16x32_bf16 v[48:51], v[144:147], v[190:193], v[48:51]
	v_mfma_f32_16x16x32_bf16 v[40:43], v[158:161], v[190:193], v[40:43]
	v_mfma_f32_16x16x32_bf16 v[32:35], v[144:147], v[198:201], v[32:35]
	v_mfma_f32_16x16x32_bf16 v[24:27], v[158:161], v[198:201], v[24:27]
	v_mfma_f32_16x16x32_bf16 v[16:19], v[144:147], v[206:209], v[16:19]
	v_mfma_f32_16x16x32_bf16 v[8:11], v[158:161], v[206:209], v[8:11]
	v_mfma_f32_16x16x32_bf16 v[60:63], v[154:157], v[186:189], v[60:63]
	v_mfma_f32_16x16x32_bf16 v[56:59], v[162:165], v[186:189], v[56:59]
	v_mfma_f32_16x16x32_bf16 v[48:51], v[154:157], v[194:197], v[48:51]
	v_mfma_f32_16x16x32_bf16 v[40:43], v[162:165], v[194:197], v[40:43]
	v_mfma_f32_16x16x32_bf16 v[32:35], v[154:157], v[202:205], v[32:35]
	v_mfma_f32_16x16x32_bf16 v[24:27], v[162:165], v[202:205], v[24:27]
	v_mfma_f32_16x16x32_bf16 v[16:19], v[154:157], v[210:213], v[16:19]
	v_mfma_f32_16x16x32_bf16 v[8:11], v[162:165], v[210:213], v[8:11]
	s_setprio 0
	s_setprio 1
	v_mfma_f32_16x16x32_bf16 v[52:55], v[166:169], v[182:185], v[52:55]
	v_mfma_f32_16x16x32_bf16 v[44:47], v[174:177], v[182:185], v[44:47]
	v_mfma_f32_16x16x32_bf16 v[36:39], v[166:169], v[190:193], v[36:39]
	v_mfma_f32_16x16x32_bf16 v[28:31], v[174:177], v[190:193], v[28:31]
	v_mfma_f32_16x16x32_bf16 v[20:23], v[166:169], v[198:201], v[20:23]
	v_mfma_f32_16x16x32_bf16 v[12:15], v[174:177], v[198:201], v[12:15]
	v_mfma_f32_16x16x32_bf16 v[4:7], v[166:169], v[206:209], v[4:7]
	v_mfma_f32_16x16x32_bf16 v[0:3], v[174:177], v[206:209], v[0:3]
	v_mfma_f32_16x16x32_bf16 v[52:55], v[170:173], v[186:189], v[52:55]
	v_mfma_f32_16x16x32_bf16 v[44:47], v[178:181], v[186:189], v[44:47]
	s_setprio 2
	s_barrier
	v_mfma_f32_16x16x32_bf16 v[36:39], v[170:173], v[194:197], v[36:39]
	v_mfma_f32_16x16x32_bf16 v[28:31], v[178:181], v[194:197], v[28:31]
	v_mfma_f32_16x16x32_bf16 v[20:23], v[170:173], v[202:205], v[20:23]
	v_mfma_f32_16x16x32_bf16 v[12:15], v[178:181], v[202:205], v[12:15]
	v_mfma_f32_16x16x32_bf16 v[4:7], v[170:173], v[210:213], v[4:7]
	v_mfma_f32_16x16x32_bf16 v[0:3], v[178:181], v[210:213], v[0:3]
	s_setprio 0
	s_add_i32 s68, 0, 0x18000
	v_add_u32_e32 v153, s68, v148
	s_add_i32 s69, 0, 0x1c000
	ds_read_b128 v[144:147], v153
	ds_read_b128 v[154:157], v153 offset:1024
	ds_read_b128 v[158:161], v153 offset:2048
	ds_read_b128 v[162:165], v153 offset:3072
	v_add_u32_e32 v153, s69, v148
	ds_read_b128 v[166:169], v153
	ds_read_b128 v[170:173], v153 offset:1024
	ds_read_b128 v[174:177], v153 offset:2048
	ds_read_b128 v[178:181], v153 offset:3072
	s_add_u32 s36, s36, 0x100000
	s_addc_u32 s37, s37, 0
	s_mov_b32 m0, s48
	v_lshl_add_u64 v[222:223], s[36:37], 0, v[128:129]
	ds_read_b128 v[182:185], v151 offset:32768
	ds_read_b128 v[186:189], v151 offset:33792
	ds_read_b128 v[190:193], v151 offset:34816
	ds_read_b128 v[194:197], v151 offset:35840
	ds_read_b128 v[198:201], v151 offset:36864
	ds_read_b128 v[202:205], v151 offset:37888
	ds_read_b128 v[206:209], v151 offset:38912
	ds_read_b128 v[210:213], v151 offset:39936
	global_load_lds_dwordx4 v[222:223], off
	v_lshl_add_u64 v[222:223], s[36:37], 0, v[132:133]
	s_mov_b32 m0, s49
	s_nop 0
	global_load_lds_dwordx4 v[222:223], off
	s_waitcnt vmcnt(8)
	s_waitcnt lgkmcnt(0)
	s_barrier
	s_setprio 1
	s_waitcnt lgkmcnt(0)
	v_mfma_f32_16x16x32_bf16 v[124:127], v[144:147], v[182:185], v[124:127]
	v_mfma_f32_16x16x32_bf16 v[120:123], v[158:161], v[182:185], v[120:123]
	v_mfma_f32_16x16x32_bf16 v[112:115], v[144:147], v[190:193], v[112:115]
	v_mfma_f32_16x16x32_bf16 v[104:107], v[158:161], v[190:193], v[104:107]
	v_mfma_f32_16x16x32_bf16 v[96:99], v[144:147], v[198:201], v[96:99]
	v_mfma_f32_16x16x32_bf16 v[88:91], v[158:161], v[198:201], v[88:91]
	v_mfma_f32_16x16x32_bf16 v[80:83], v[144:147], v[206:209], v[80:83]
	v_mfma_f32_16x16x32_bf16 v[72:75], v[158:161], v[206:209], v[72:75]
	v_mfma_f32_16x16x32_bf16 v[124:127], v[154:157], v[186:189], v[124:127]
	v_mfma_f32_16x16x32_bf16 v[120:123], v[162:165], v[186:189], v[120:123]
	v_mfma_f32_16x16x32_bf16 v[112:115], v[154:157], v[194:197], v[112:115]
	v_mfma_f32_16x16x32_bf16 v[104:107], v[162:165], v[194:197], v[104:107]
	v_mfma_f32_16x16x32_bf16 v[96:99], v[154:157], v[202:205], v[96:99]
	v_mfma_f32_16x16x32_bf16 v[88:91], v[162:165], v[202:205], v[88:91]
	v_mfma_f32_16x16x32_bf16 v[80:83], v[154:157], v[210:213], v[80:83]
	v_mfma_f32_16x16x32_bf16 v[72:75], v[162:165], v[210:213], v[72:75]
	s_setprio 0
	s_setprio 1
	v_mfma_f32_16x16x32_bf16 v[116:119], v[166:169], v[182:185], v[116:119]
	v_mfma_f32_16x16x32_bf16 v[108:111], v[174:177], v[182:185], v[108:111]
	v_mfma_f32_16x16x32_bf16 v[100:103], v[166:169], v[190:193], v[100:103]
	v_mfma_f32_16x16x32_bf16 v[92:95], v[174:177], v[190:193], v[92:95]
	v_mfma_f32_16x16x32_bf16 v[84:87], v[166:169], v[198:201], v[84:87]
	v_mfma_f32_16x16x32_bf16 v[76:79], v[174:177], v[198:201], v[76:79]
	v_mfma_f32_16x16x32_bf16 v[68:71], v[166:169], v[206:209], v[68:71]
	v_mfma_f32_16x16x32_bf16 v[64:67], v[174:177], v[206:209], v[64:67]
	v_mfma_f32_16x16x32_bf16 v[116:119], v[170:173], v[186:189], v[116:119]
	v_mfma_f32_16x16x32_bf16 v[108:111], v[178:181], v[186:189], v[108:111]
	s_setprio 2
	s_barrier
	v_mfma_f32_16x16x32_bf16 v[100:103], v[170:173], v[194:197], v[100:103]
	v_mfma_f32_16x16x32_bf16 v[92:95], v[178:181], v[194:197], v[92:95]
	v_mfma_f32_16x16x32_bf16 v[84:87], v[170:173], v[202:205], v[84:87]
	v_mfma_f32_16x16x32_bf16 v[76:79], v[178:181], v[202:205], v[76:79]
	v_mfma_f32_16x16x32_bf16 v[68:71], v[170:173], v[210:213], v[68:71]
	v_mfma_f32_16x16x32_bf16 v[64:67], v[178:181], v[210:213], v[64:67]
	s_setprio 0
	s_add_i32 s36, s68, s46
	v_lshl_add_u64 v[214:215], v[214:215], 0, s[14:15]
	s_mov_b32 m0, s36
	ds_read_b128 v[182:185], v151 offset:49152
	ds_read_b128 v[186:189], v151 offset:50176
	ds_read_b128 v[190:193], v151 offset:51200
	ds_read_b128 v[194:197], v151 offset:52224
	ds_read_b128 v[198:201], v151 offset:53248
	ds_read_b128 v[202:205], v151 offset:54272
	ds_read_b128 v[206:209], v151 offset:55296
	ds_read_b128 v[210:213], v151 offset:56320
	global_load_lds_dwordx4 v[214:215], off
	s_add_i32 m0, s36, 0x2000
	s_add_u32 s30, s30, 0x100080
	v_lshl_add_u64 v[214:215], v[216:217], 0, s[14:15]
	s_addc_u32 s31, s31, 0
	s_add_i32 s36, s69, s46
	global_load_lds_dwordx4 v[214:215], off
	v_lshl_add_u64 v[214:215], s[30:31], 0, v[130:131]
	s_mov_b32 m0, s36
	s_nop 0
	global_load_lds_dwordx4 v[214:215], off
	v_lshl_add_u64 v[214:215], s[30:31], 0, v[134:135]
	s_add_i32 m0, s36, 0x2000
	s_nop 0
	global_load_lds_dwordx4 v[214:215], off
	v_lshl_add_u64 v[214:215], v[218:219], 0, s[14:15]
	s_mov_b32 m0, s53
	s_nop 0
	global_load_lds_dwordx4 v[214:215], off
	v_lshl_add_u64 v[214:215], v[220:221], 0, s[14:15]
	s_mov_b32 m0, s54
	s_nop 0
	global_load_lds_dwordx4 v[214:215], off
	s_waitcnt vmcnt(8)
	s_waitcnt lgkmcnt(0)
	s_barrier
	s_setprio 1
	s_waitcnt lgkmcnt(0)
	v_mfma_f32_16x16x32_bf16 v[60:63], v[144:147], v[182:185], v[60:63]
	v_mfma_f32_16x16x32_bf16 v[56:59], v[158:161], v[182:185], v[56:59]
	v_mfma_f32_16x16x32_bf16 v[48:51], v[144:147], v[190:193], v[48:51]
	v_mfma_f32_16x16x32_bf16 v[40:43], v[158:161], v[190:193], v[40:43]
	v_mfma_f32_16x16x32_bf16 v[32:35], v[144:147], v[198:201], v[32:35]
	v_mfma_f32_16x16x32_bf16 v[24:27], v[158:161], v[198:201], v[24:27]
	v_mfma_f32_16x16x32_bf16 v[16:19], v[144:147], v[206:209], v[16:19]
	v_mfma_f32_16x16x32_bf16 v[8:11], v[158:161], v[206:209], v[8:11]
	v_mfma_f32_16x16x32_bf16 v[60:63], v[154:157], v[186:189], v[60:63]
	v_mfma_f32_16x16x32_bf16 v[56:59], v[162:165], v[186:189], v[56:59]
	v_mfma_f32_16x16x32_bf16 v[48:51], v[154:157], v[194:197], v[48:51]
	v_mfma_f32_16x16x32_bf16 v[40:43], v[162:165], v[194:197], v[40:43]
	v_mfma_f32_16x16x32_bf16 v[32:35], v[154:157], v[202:205], v[32:35]
	v_mfma_f32_16x16x32_bf16 v[24:27], v[162:165], v[202:205], v[24:27]
	v_mfma_f32_16x16x32_bf16 v[16:19], v[154:157], v[210:213], v[16:19]
	v_mfma_f32_16x16x32_bf16 v[8:11], v[162:165], v[210:213], v[8:11]
	s_setprio 0
	s_setprio 1
	v_mfma_f32_16x16x32_bf16 v[52:55], v[166:169], v[182:185], v[52:55]
	v_mfma_f32_16x16x32_bf16 v[44:47], v[174:177], v[182:185], v[44:47]
	v_mfma_f32_16x16x32_bf16 v[36:39], v[166:169], v[190:193], v[36:39]
	v_mfma_f32_16x16x32_bf16 v[28:31], v[174:177], v[190:193], v[28:31]
	v_mfma_f32_16x16x32_bf16 v[20:23], v[166:169], v[198:201], v[20:23]
	v_mfma_f32_16x16x32_bf16 v[12:15], v[174:177], v[198:201], v[12:15]
	v_mfma_f32_16x16x32_bf16 v[4:7], v[166:169], v[206:209], v[4:7]
	v_mfma_f32_16x16x32_bf16 v[0:3], v[174:177], v[206:209], v[0:3]
	v_mfma_f32_16x16x32_bf16 v[52:55], v[170:173], v[186:189], v[52:55]
	v_mfma_f32_16x16x32_bf16 v[44:47], v[178:181], v[186:189], v[44:47]
	s_setprio 2
	s_barrier
	v_mfma_f32_16x16x32_bf16 v[36:39], v[170:173], v[194:197], v[36:39]
	v_mfma_f32_16x16x32_bf16 v[28:31], v[178:181], v[194:197], v[28:31]
	v_mfma_f32_16x16x32_bf16 v[20:23], v[170:173], v[202:205], v[20:23]
	v_mfma_f32_16x16x32_bf16 v[12:15], v[178:181], v[202:205], v[12:15]
	v_mfma_f32_16x16x32_bf16 v[4:7], v[170:173], v[210:213], v[4:7]
	v_mfma_f32_16x16x32_bf16 v[0:3], v[178:181], v[210:213], v[0:3]
	s_setprio 0
	s_add_i32 s67, s67, 2
	s_add_u32 s28, s28, 0x100
	s_addc_u32 s29, s29, 0
	s_add_u32 s61, s61, 0x100
	s_addc_u32 s62, s62, 0
	s_cmp_gt_u32 s67, 61
	s_cbranch_scc0 .LBB0_229

.LBB0_633:
	v_add_u32_e32 v160, s68, v164
	v_add_u32_e32 v178, s69, v164
	s_add_u32 s48, s38, s46
	ds_read_b128 v[148:151], v160
	ds_read_b128 v[152:155], v160 offset:1024
	ds_read_b128 v[156:159], v160 offset:2048
	ds_read_b128 v[160:163], v160 offset:3072
	ds_read_b128 v[166:169], v178
	ds_read_b128 v[170:173], v178 offset:1024
	ds_read_b128 v[174:177], v178 offset:2048
	ds_read_b128 v[178:181], v178 offset:3072
	s_addc_u32 s49, s39, s47
	s_add_u32 s48, s48, 0x100
	s_addc_u32 s49, s49, 0
	s_add_u32 s67, s74, s46
	s_addc_u32 s77, s75, s47
	s_cmpk_eq_i32 s46, 0xf00
	s_cselect_b32 s51, s29, s49
	s_cselect_b32 s50, s71, s48
	s_cselect_b32 s49, s72, s77
	s_cselect_b32 s48, s73, s67
	v_lshl_add_u64 v[214:215], v[144:145], 0, s[46:47]
	s_add_i32 m0, s54, 0xc000
	ds_read_b128 v[182:185], v165
	ds_read_b128 v[186:189], v165 offset:1024
	ds_read_b128 v[190:193], v165 offset:2048
	ds_read_b128 v[194:197], v165 offset:3072
	ds_read_b128 v[198:201], v165 offset:4096
	ds_read_b128 v[202:205], v165 offset:5120
	ds_read_b128 v[206:209], v165 offset:6144
	ds_read_b128 v[210:213], v165 offset:7168
	global_load_lds_dwordx4 v[214:215], off
	v_lshl_add_u64 v[214:215], v[146:147], 0, s[46:47]
	s_add_i32 m0, s54, 0xe000
	s_nop 0
	global_load_lds_dwordx4 v[214:215], off
	s_waitcnt vmcnt(8)
	s_waitcnt lgkmcnt(0)
	s_barrier
	s_setprio 1
	s_waitcnt lgkmcnt(0)
	v_mfma_i32_16x16x64_i8 v[124:127], v[148:151], v[182:185], v[124:127]
	v_mfma_i32_16x16x64_i8 v[120:123], v[156:159], v[182:185], v[120:123]
	v_mfma_i32_16x16x64_i8 v[108:111], v[148:151], v[190:193], v[108:111]
	v_mfma_i32_16x16x64_i8 v[104:107], v[156:159], v[190:193], v[104:107]
	v_mfma_i32_16x16x64_i8 v[92:95], v[148:151], v[198:201], v[92:95]
	v_mfma_i32_16x16x64_i8 v[88:91], v[156:159], v[198:201], v[88:91]
	v_mfma_i32_16x16x64_i8 v[76:79], v[148:151], v[206:209], v[76:79]
	v_mfma_i32_16x16x64_i8 v[72:75], v[156:159], v[206:209], v[72:75]
	v_mfma_i32_16x16x64_i8 v[124:127], v[152:155], v[186:189], v[124:127]
	v_mfma_i32_16x16x64_i8 v[120:123], v[160:163], v[186:189], v[120:123]
	v_mfma_i32_16x16x64_i8 v[108:111], v[152:155], v[194:197], v[108:111]
	v_mfma_i32_16x16x64_i8 v[104:107], v[160:163], v[194:197], v[104:107]
	v_mfma_i32_16x16x64_i8 v[92:95], v[152:155], v[202:205], v[92:95]
	v_mfma_i32_16x16x64_i8 v[88:91], v[160:163], v[202:205], v[88:91]
	v_mfma_i32_16x16x64_i8 v[76:79], v[152:155], v[210:213], v[76:79]
	v_mfma_i32_16x16x64_i8 v[72:75], v[160:163], v[210:213], v[72:75]
	s_setprio 0
	s_setprio 1
	v_mfma_i32_16x16x64_i8 v[116:119], v[166:169], v[182:185], v[116:119]
	v_mfma_i32_16x16x64_i8 v[112:115], v[174:177], v[182:185], v[112:115]
	v_mfma_i32_16x16x64_i8 v[100:103], v[166:169], v[190:193], v[100:103]
	v_mfma_i32_16x16x64_i8 v[96:99], v[174:177], v[190:193], v[96:99]
	v_mfma_i32_16x16x64_i8 v[84:87], v[166:169], v[198:201], v[84:87]
	v_mfma_i32_16x16x64_i8 v[80:83], v[174:177], v[198:201], v[80:83]
	v_mfma_i32_16x16x64_i8 v[68:71], v[166:169], v[206:209], v[68:71]
	v_mfma_i32_16x16x64_i8 v[64:67], v[174:177], v[206:209], v[64:67]
	v_mfma_i32_16x16x64_i8 v[116:119], v[170:173], v[186:189], v[116:119]
	v_mfma_i32_16x16x64_i8 v[112:115], v[178:181], v[186:189], v[112:115]
	v_mfma_i32_16x16x64_i8 v[100:103], v[170:173], v[194:197], v[100:103]
	s_setprio 2
	s_barrier
	v_mfma_i32_16x16x64_i8 v[96:99], v[178:181], v[194:197], v[96:99]
	v_mfma_i32_16x16x64_i8 v[84:87], v[170:173], v[202:205], v[84:87]
	v_mfma_i32_16x16x64_i8 v[80:83], v[178:181], v[202:205], v[80:83]
	v_mfma_i32_16x16x64_i8 v[68:71], v[170:173], v[210:213], v[68:71]
	v_mfma_i32_16x16x64_i8 v[64:67], v[178:181], v[210:213], v[64:67]
	s_setprio 0
	s_add_i32 s67, s68, s45
	v_lshl_add_u64 v[214:215], s[48:49], 0, v[132:133]
	s_mov_b32 m0, s67
	ds_read_b128 v[182:185], v165 offset:16384
	ds_read_b128 v[186:189], v165 offset:17408
	ds_read_b128 v[190:193], v165 offset:18432
	ds_read_b128 v[194:197], v165 offset:19456
	ds_read_b128 v[198:201], v165 offset:20480
	ds_read_b128 v[202:205], v165 offset:21504
	ds_read_b128 v[206:209], v165 offset:22528
	ds_read_b128 v[210:213], v165 offset:23552
	global_load_lds_dwordx4 v[214:215], off
	s_add_i32 m0, s67, 0x2000
	s_add_u32 s78, s48, 0x80000
	v_lshl_add_u64 v[216:217], s[48:49], 0, v[128:129]
	s_addc_u32 s79, s49, 0
	s_add_i32 s67, s69, s45
	global_load_lds_dwordx4 v[216:217], off
	v_lshl_add_u64 v[218:219], s[78:79], 0, v[132:133]
	s_mov_b32 m0, s67
	v_lshl_add_u64 v[220:221], s[50:51], 0, v[130:131]
	global_load_lds_dwordx4 v[218:219], off
	v_lshl_add_u64 v[218:219], s[78:79], 0, v[128:129]
	s_add_i32 m0, s67, 0x2000
	s_nop 0
	global_load_lds_dwordx4 v[218:219], off
	v_lshl_add_u64 v[218:219], s[50:51], 0, v[134:135]
	s_mov_b32 m0, s54
	s_nop 0
	global_load_lds_dwordx4 v[218:219], off
	s_mov_b32 m0, s55
	s_nop 0
	global_load_lds_dwordx4 v[220:221], off
	s_waitcnt vmcnt(8)
	s_waitcnt lgkmcnt(0)
	s_barrier
	s_setprio 1
	s_waitcnt lgkmcnt(0)
	v_mfma_i32_16x16x64_i8 v[60:63], v[148:151], v[182:185], v[60:63]
	v_mfma_i32_16x16x64_i8 v[56:59], v[156:159], v[182:185], v[56:59]
	v_mfma_i32_16x16x64_i8 v[44:47], v[148:151], v[190:193], v[44:47]
	v_mfma_i32_16x16x64_i8 v[40:43], v[156:159], v[190:193], v[40:43]
	v_mfma_i32_16x16x64_i8 v[28:31], v[148:151], v[198:201], v[28:31]
	v_mfma_i32_16x16x64_i8 v[24:27], v[156:159], v[198:201], v[24:27]
	v_mfma_i32_16x16x64_i8 v[12:15], v[148:151], v[206:209], v[12:15]
	v_mfma_i32_16x16x64_i8 v[8:11], v[156:159], v[206:209], v[8:11]
	v_mfma_i32_16x16x64_i8 v[60:63], v[152:155], v[186:189], v[60:63]
	v_mfma_i32_16x16x64_i8 v[56:59], v[160:163], v[186:189], v[56:59]
	v_mfma_i32_16x16x64_i8 v[44:47], v[152:155], v[194:197], v[44:47]
	v_mfma_i32_16x16x64_i8 v[40:43], v[160:163], v[194:197], v[40:43]
	v_mfma_i32_16x16x64_i8 v[28:31], v[152:155], v[202:205], v[28:31]
	v_mfma_i32_16x16x64_i8 v[24:27], v[160:163], v[202:205], v[24:27]
	v_mfma_i32_16x16x64_i8 v[12:15], v[152:155], v[210:213], v[12:15]
	v_mfma_i32_16x16x64_i8 v[8:11], v[160:163], v[210:213], v[8:11]
	s_setprio 0
	s_setprio 1
	v_mfma_i32_16x16x64_i8 v[52:55], v[166:169], v[182:185], v[52:55]
	v_mfma_i32_16x16x64_i8 v[48:51], v[174:177], v[182:185], v[48:51]
	v_mfma_i32_16x16x64_i8 v[36:39], v[166:169], v[190:193], v[36:39]
	v_mfma_i32_16x16x64_i8 v[32:35], v[174:177], v[190:193], v[32:35]
	v_mfma_i32_16x16x64_i8 v[20:23], v[166:169], v[198:201], v[20:23]
	v_mfma_i32_16x16x64_i8 v[16:19], v[174:177], v[198:201], v[16:19]
	v_mfma_i32_16x16x64_i8 v[4:7], v[166:169], v[206:209], v[4:7]
	v_mfma_i32_16x16x64_i8 v[0:3], v[174:177], v[206:209], v[0:3]
	v_mfma_i32_16x16x64_i8 v[52:55], v[170:173], v[186:189], v[52:55]
	v_mfma_i32_16x16x64_i8 v[48:51], v[178:181], v[186:189], v[48:51]
	v_mfma_i32_16x16x64_i8 v[36:39], v[170:173], v[194:197], v[36:39]
	s_setprio 2
	s_barrier
	v_mfma_i32_16x16x64_i8 v[32:35], v[178:181], v[194:197], v[32:35]
	v_mfma_i32_16x16x64_i8 v[20:23], v[170:173], v[202:205], v[20:23]
	v_mfma_i32_16x16x64_i8 v[16:19], v[178:181], v[202:205], v[16:19]
	v_mfma_i32_16x16x64_i8 v[4:7], v[170:173], v[210:213], v[4:7]
	v_mfma_i32_16x16x64_i8 v[0:3], v[178:181], v[210:213], v[0:3]
	s_setprio 0
	s_add_i32 s67, 0, 0x18000
	s_add_i32 s77, 0, 0x1c000
	v_add_u32_e32 v160, s67, v164
	v_add_u32_e32 v178, s77, v164
	ds_read_b128 v[148:151], v160
	ds_read_b128 v[152:155], v160 offset:1024
	ds_read_b128 v[156:159], v160 offset:2048
	ds_read_b128 v[160:163], v160 offset:3072
	ds_read_b128 v[166:169], v178
	ds_read_b128 v[170:173], v178 offset:1024
	ds_read_b128 v[174:177], v178 offset:2048
	ds_read_b128 v[178:181], v178 offset:3072
	s_add_u32 s50, s50, 0x80000
	s_addc_u32 s51, s51, 0
	s_mov_b32 m0, s56
	v_lshl_add_u64 v[222:223], s[50:51], 0, v[134:135]
	ds_read_b128 v[182:185], v165 offset:32768
	ds_read_b128 v[186:189], v165 offset:33792
	ds_read_b128 v[190:193], v165 offset:34816
	ds_read_b128 v[194:197], v165 offset:35840
	ds_read_b128 v[198:201], v165 offset:36864
	ds_read_b128 v[202:205], v165 offset:37888
	ds_read_b128 v[206:209], v165 offset:38912
	ds_read_b128 v[210:213], v165 offset:39936
	global_load_lds_dwordx4 v[222:223], off
	v_lshl_add_u64 v[222:223], s[50:51], 0, v[130:131]
	s_mov_b32 m0, s57
	s_nop 0
	global_load_lds_dwordx4 v[222:223], off
	s_waitcnt vmcnt(8)
	s_waitcnt lgkmcnt(0)
	s_barrier
	s_setprio 1
	s_waitcnt lgkmcnt(0)
	v_mfma_i32_16x16x64_i8 v[124:127], v[148:151], v[182:185], v[124:127]
	v_mfma_i32_16x16x64_i8 v[120:123], v[156:159], v[182:185], v[120:123]
	v_mfma_i32_16x16x64_i8 v[108:111], v[148:151], v[190:193], v[108:111]
	v_mfma_i32_16x16x64_i8 v[104:107], v[156:159], v[190:193], v[104:107]
	v_mfma_i32_16x16x64_i8 v[92:95], v[148:151], v[198:201], v[92:95]
	v_mfma_i32_16x16x64_i8 v[88:91], v[156:159], v[198:201], v[88:91]
	v_mfma_i32_16x16x64_i8 v[76:79], v[148:151], v[206:209], v[76:79]
	v_mfma_i32_16x16x64_i8 v[72:75], v[156:159], v[206:209], v[72:75]
	v_mfma_i32_16x16x64_i8 v[124:127], v[152:155], v[186:189], v[124:127]
	v_mfma_i32_16x16x64_i8 v[120:123], v[160:163], v[186:189], v[120:123]
	v_mfma_i32_16x16x64_i8 v[108:111], v[152:155], v[194:197], v[108:111]
	v_mfma_i32_16x16x64_i8 v[104:107], v[160:163], v[194:197], v[104:107]
	v_mfma_i32_16x16x64_i8 v[92:95], v[152:155], v[202:205], v[92:95]
	v_mfma_i32_16x16x64_i8 v[88:91], v[160:163], v[202:205], v[88:91]
	v_mfma_i32_16x16x64_i8 v[76:79], v[152:155], v[210:213], v[76:79]
	v_mfma_i32_16x16x64_i8 v[72:75], v[160:163], v[210:213], v[72:75]
	s_setprio 0
	s_setprio 1
	v_mfma_i32_16x16x64_i8 v[116:119], v[166:169], v[182:185], v[116:119]
	v_mfma_i32_16x16x64_i8 v[112:115], v[174:177], v[182:185], v[112:115]
	v_mfma_i32_16x16x64_i8 v[100:103], v[166:169], v[190:193], v[100:103]
	v_mfma_i32_16x16x64_i8 v[96:99], v[174:177], v[190:193], v[96:99]
	v_mfma_i32_16x16x64_i8 v[84:87], v[166:169], v[198:201], v[84:87]
	v_mfma_i32_16x16x64_i8 v[80:83], v[174:177], v[198:201], v[80:83]
	v_mfma_i32_16x16x64_i8 v[68:71], v[166:169], v[206:209], v[68:71]
	v_mfma_i32_16x16x64_i8 v[64:67], v[174:177], v[206:209], v[64:67]
	v_mfma_i32_16x16x64_i8 v[116:119], v[170:173], v[186:189], v[116:119]
	v_mfma_i32_16x16x64_i8 v[112:115], v[178:181], v[186:189], v[112:115]
	v_mfma_i32_16x16x64_i8 v[100:103], v[170:173], v[194:197], v[100:103]
	s_setprio 2
	s_barrier
	v_mfma_i32_16x16x64_i8 v[96:99], v[178:181], v[194:197], v[96:99]
	v_mfma_i32_16x16x64_i8 v[84:87], v[170:173], v[202:205], v[84:87]
	v_mfma_i32_16x16x64_i8 v[80:83], v[178:181], v[202:205], v[80:83]
	v_mfma_i32_16x16x64_i8 v[68:71], v[170:173], v[210:213], v[68:71]
	v_mfma_i32_16x16x64_i8 v[64:67], v[178:181], v[210:213], v[64:67]
	s_setprio 0
	s_add_i32 s50, s67, s45
	v_lshl_add_u64 v[214:215], v[214:215], 0, s[18:19]
	s_mov_b32 m0, s50
	ds_read_b128 v[182:185], v165 offset:49152
	ds_read_b128 v[186:189], v165 offset:50176
	ds_read_b128 v[190:193], v165 offset:51200
	ds_read_b128 v[194:197], v165 offset:52224
	ds_read_b128 v[198:201], v165 offset:53248
	ds_read_b128 v[202:205], v165 offset:54272
	ds_read_b128 v[206:209], v165 offset:55296
	ds_read_b128 v[210:213], v165 offset:56320
	global_load_lds_dwordx4 v[214:215], off
	s_add_i32 m0, s50, 0x2000
	s_add_u32 s48, s48, 0x80080
	v_lshl_add_u64 v[214:215], v[216:217], 0, s[18:19]
	s_addc_u32 s49, s49, 0
	s_add_i32 s50, s77, s45
	global_load_lds_dwordx4 v[214:215], off
	v_lshl_add_u64 v[214:215], s[48:49], 0, v[132:133]
	s_mov_b32 m0, s50
	s_nop 0
	global_load_lds_dwordx4 v[214:215], off
	v_lshl_add_u64 v[214:215], s[48:49], 0, v[128:129]
	s_add_i32 m0, s50, 0x2000
	s_nop 0
	global_load_lds_dwordx4 v[214:215], off
	v_lshl_add_u64 v[214:215], v[218:219], 0, s[18:19]
	s_mov_b32 m0, s60
	s_nop 0
	global_load_lds_dwordx4 v[214:215], off
	v_lshl_add_u64 v[214:215], v[220:221], 0, s[18:19]
	s_mov_b32 m0, s61
	s_nop 0
	global_load_lds_dwordx4 v[214:215], off
	s_waitcnt vmcnt(8)
	s_waitcnt lgkmcnt(0)
	s_barrier
	s_setprio 1
	s_waitcnt lgkmcnt(0)
	v_mfma_i32_16x16x64_i8 v[60:63], v[148:151], v[182:185], v[60:63]
	v_mfma_i32_16x16x64_i8 v[56:59], v[156:159], v[182:185], v[56:59]
	v_mfma_i32_16x16x64_i8 v[44:47], v[148:151], v[190:193], v[44:47]
	v_mfma_i32_16x16x64_i8 v[40:43], v[156:159], v[190:193], v[40:43]
	v_mfma_i32_16x16x64_i8 v[28:31], v[148:151], v[198:201], v[28:31]
	v_mfma_i32_16x16x64_i8 v[24:27], v[156:159], v[198:201], v[24:27]
	v_mfma_i32_16x16x64_i8 v[12:15], v[148:151], v[206:209], v[12:15]
	v_mfma_i32_16x16x64_i8 v[8:11], v[156:159], v[206:209], v[8:11]
	v_mfma_i32_16x16x64_i8 v[60:63], v[152:155], v[186:189], v[60:63]
	v_mfma_i32_16x16x64_i8 v[56:59], v[160:163], v[186:189], v[56:59]
	v_mfma_i32_16x16x64_i8 v[44:47], v[152:155], v[194:197], v[44:47]
	v_mfma_i32_16x16x64_i8 v[40:43], v[160:163], v[194:197], v[40:43]
	v_mfma_i32_16x16x64_i8 v[28:31], v[152:155], v[202:205], v[28:31]
	v_mfma_i32_16x16x64_i8 v[24:27], v[160:163], v[202:205], v[24:27]
	v_mfma_i32_16x16x64_i8 v[12:15], v[152:155], v[210:213], v[12:15]
	v_mfma_i32_16x16x64_i8 v[8:11], v[160:163], v[210:213], v[8:11]
	s_setprio 0
	s_setprio 1
	v_mfma_i32_16x16x64_i8 v[52:55], v[166:169], v[182:185], v[52:55]
	v_mfma_i32_16x16x64_i8 v[48:51], v[174:177], v[182:185], v[48:51]
	v_mfma_i32_16x16x64_i8 v[36:39], v[166:169], v[190:193], v[36:39]
	v_mfma_i32_16x16x64_i8 v[32:35], v[174:177], v[190:193], v[32:35]
	v_mfma_i32_16x16x64_i8 v[20:23], v[166:169], v[198:201], v[20:23]
	v_mfma_i32_16x16x64_i8 v[16:19], v[174:177], v[198:201], v[16:19]
	v_mfma_i32_16x16x64_i8 v[4:7], v[166:169], v[206:209], v[4:7]
	v_mfma_i32_16x16x64_i8 v[0:3], v[174:177], v[206:209], v[0:3]
	v_mfma_i32_16x16x64_i8 v[52:55], v[170:173], v[186:189], v[52:55]
	v_mfma_i32_16x16x64_i8 v[48:51], v[178:181], v[186:189], v[48:51]
	v_mfma_i32_16x16x64_i8 v[36:39], v[170:173], v[194:197], v[36:39]
	s_setprio 2
	s_barrier
	v_mfma_i32_16x16x64_i8 v[32:35], v[178:181], v[194:197], v[32:35]
	v_mfma_i32_16x16x64_i8 v[20:23], v[170:173], v[202:205], v[20:23]
	v_mfma_i32_16x16x64_i8 v[16:19], v[178:181], v[202:205], v[16:19]
	v_mfma_i32_16x16x64_i8 v[4:7], v[170:173], v[210:213], v[4:7]
	v_mfma_i32_16x16x64_i8 v[0:3], v[178:181], v[210:213], v[0:3]
	s_setprio 0
	s_add_i32 s76, s76, 2
	s_add_u32 s46, s46, 0x100
	s_addc_u32 s47, s47, 0
	s_cmp_gt_u32 s76, 29
	s_cbranch_scc1 .LBB0_636

.LBB0_771:
	ds_read_b128 v[144:147], v153
	ds_read_b128 v[148:151], v153 offset:1024
	ds_read_b128 v[156:159], v153 offset:2048
	ds_read_b128 v[160:163], v153 offset:3072
	ds_read_b128 v[164:167], v154
	ds_read_b128 v[168:171], v154 offset:1024
	ds_read_b128 v[172:175], v154 offset:2048
	ds_read_b128 v[176:179], v154 offset:3072
	s_add_u32 s56, s54, 0xfff80080
	s_addc_u32 s57, s55, -1
	s_cmp_eq_u32 s79, 28
	s_cselect_b32 s59, s47, s57
	s_cselect_b32 s58, s75, s56
	s_cselect_b32 s57, s39, s78
	s_cselect_b32 s56, s76, s77
	v_lshl_add_u64 v[212:213], s[54:55], 0, v[136:137]
	s_add_i32 m0, s37, 0xc000
	ds_read_b128 v[180:183], v155
	ds_read_b128 v[184:187], v155 offset:1024
	ds_read_b128 v[188:191], v155 offset:2048
	ds_read_b128 v[192:195], v155 offset:3072
	ds_read_b128 v[196:199], v155 offset:4096
	ds_read_b128 v[200:203], v155 offset:5120
	ds_read_b128 v[204:207], v155 offset:6144
	ds_read_b128 v[208:211], v155 offset:7168
	global_load_lds_dwordx4 v[212:213], off
	v_lshl_add_u64 v[212:213], s[54:55], 0, v[138:139]
	s_add_i32 m0, s37, 0xe000
	s_nop 0
	global_load_lds_dwordx4 v[212:213], off
	s_waitcnt vmcnt(8)
	s_waitcnt lgkmcnt(0)
	s_barrier
	s_setprio 1
	s_waitcnt lgkmcnt(0)
	v_mfma_i32_16x16x64_i8 v[124:127], v[144:147], v[180:183], v[124:127]
	v_mfma_i32_16x16x64_i8 v[120:123], v[156:159], v[180:183], v[120:123]
	v_mfma_i32_16x16x64_i8 v[108:111], v[144:147], v[188:191], v[108:111]
	v_mfma_i32_16x16x64_i8 v[104:107], v[156:159], v[188:191], v[104:107]
	v_mfma_i32_16x16x64_i8 v[92:95], v[144:147], v[196:199], v[92:95]
	v_mfma_i32_16x16x64_i8 v[88:91], v[156:159], v[196:199], v[88:91]
	v_mfma_i32_16x16x64_i8 v[76:79], v[144:147], v[204:207], v[76:79]
	v_mfma_i32_16x16x64_i8 v[72:75], v[156:159], v[204:207], v[72:75]
	v_mfma_i32_16x16x64_i8 v[124:127], v[148:151], v[184:187], v[124:127]
	v_mfma_i32_16x16x64_i8 v[120:123], v[160:163], v[184:187], v[120:123]
	v_mfma_i32_16x16x64_i8 v[108:111], v[148:151], v[192:195], v[108:111]
	v_mfma_i32_16x16x64_i8 v[104:107], v[160:163], v[192:195], v[104:107]
	v_mfma_i32_16x16x64_i8 v[92:95], v[148:151], v[200:203], v[92:95]
	v_mfma_i32_16x16x64_i8 v[88:91], v[160:163], v[200:203], v[88:91]
	v_mfma_i32_16x16x64_i8 v[76:79], v[148:151], v[208:211], v[76:79]
	v_mfma_i32_16x16x64_i8 v[72:75], v[160:163], v[208:211], v[72:75]
	s_setprio 0
	s_setprio 1
	v_mfma_i32_16x16x64_i8 v[116:119], v[164:167], v[180:183], v[116:119]
	v_mfma_i32_16x16x64_i8 v[112:115], v[172:175], v[180:183], v[112:115]
	v_mfma_i32_16x16x64_i8 v[100:103], v[164:167], v[188:191], v[100:103]
	v_mfma_i32_16x16x64_i8 v[96:99], v[172:175], v[188:191], v[96:99]
	v_mfma_i32_16x16x64_i8 v[84:87], v[164:167], v[196:199], v[84:87]
	v_mfma_i32_16x16x64_i8 v[80:83], v[172:175], v[196:199], v[80:83]
	v_mfma_i32_16x16x64_i8 v[68:71], v[164:167], v[204:207], v[68:71]
	v_mfma_i32_16x16x64_i8 v[64:67], v[172:175], v[204:207], v[64:67]
	v_mfma_i32_16x16x64_i8 v[116:119], v[168:171], v[184:187], v[116:119]
	v_mfma_i32_16x16x64_i8 v[112:115], v[176:179], v[184:187], v[112:115]
	v_mfma_i32_16x16x64_i8 v[100:103], v[168:171], v[192:195], v[100:103]
	s_setprio 2
	s_barrier
	v_mfma_i32_16x16x64_i8 v[96:99], v[176:179], v[192:195], v[96:99]
	v_mfma_i32_16x16x64_i8 v[84:87], v[168:171], v[200:203], v[84:87]
	v_mfma_i32_16x16x64_i8 v[80:83], v[176:179], v[200:203], v[80:83]
	v_mfma_i32_16x16x64_i8 v[68:71], v[168:171], v[208:211], v[68:71]
	v_mfma_i32_16x16x64_i8 v[64:67], v[176:179], v[208:211], v[64:67]
	s_setprio 0
	s_add_i32 s80, s72, s34
	v_lshl_add_u64 v[212:213], s[56:57], 0, v[132:133]
	s_mov_b32 m0, s80
	ds_read_b128 v[180:183], v155 offset:16384
	ds_read_b128 v[184:187], v155 offset:17408
	ds_read_b128 v[188:191], v155 offset:18432
	ds_read_b128 v[192:195], v155 offset:19456
	ds_read_b128 v[196:199], v155 offset:20480
	ds_read_b128 v[200:203], v155 offset:21504
	ds_read_b128 v[204:207], v155 offset:22528
	ds_read_b128 v[208:211], v155 offset:23552
	global_load_lds_dwordx4 v[212:213], off
	s_add_i32 m0, s80, 0x2000
	s_add_u32 s80, s56, 0x80000
	v_lshl_add_u64 v[214:215], s[56:57], 0, v[128:129]
	s_addc_u32 s81, s57, 0
	s_add_i32 s82, s73, s34
	global_load_lds_dwordx4 v[214:215], off
	v_lshl_add_u64 v[216:217], s[80:81], 0, v[132:133]
	s_mov_b32 m0, s82
	v_lshl_add_u64 v[218:219], s[58:59], 0, v[130:131]
	global_load_lds_dwordx4 v[216:217], off
	v_lshl_add_u64 v[216:217], s[80:81], 0, v[128:129]
	s_add_i32 m0, s82, 0x2000
	s_nop 0
	global_load_lds_dwordx4 v[216:217], off
	v_lshl_add_u64 v[216:217], s[58:59], 0, v[134:135]
	s_mov_b32 m0, s37
	s_nop 0
	global_load_lds_dwordx4 v[216:217], off
	s_mov_b32 m0, s45
	s_nop 0
	global_load_lds_dwordx4 v[218:219], off
	s_waitcnt vmcnt(8)
	s_waitcnt lgkmcnt(0)
	s_barrier
	s_setprio 1
	s_waitcnt lgkmcnt(0)
	v_mfma_i32_16x16x64_i8 v[60:63], v[144:147], v[180:183], v[60:63]
	v_mfma_i32_16x16x64_i8 v[56:59], v[156:159], v[180:183], v[56:59]
	v_mfma_i32_16x16x64_i8 v[44:47], v[144:147], v[188:191], v[44:47]
	v_mfma_i32_16x16x64_i8 v[40:43], v[156:159], v[188:191], v[40:43]
	v_mfma_i32_16x16x64_i8 v[28:31], v[144:147], v[196:199], v[28:31]
	v_mfma_i32_16x16x64_i8 v[24:27], v[156:159], v[196:199], v[24:27]
	v_mfma_i32_16x16x64_i8 v[12:15], v[144:147], v[204:207], v[12:15]
	v_mfma_i32_16x16x64_i8 v[8:11], v[156:159], v[204:207], v[8:11]
	v_mfma_i32_16x16x64_i8 v[60:63], v[148:151], v[184:187], v[60:63]
	v_mfma_i32_16x16x64_i8 v[56:59], v[160:163], v[184:187], v[56:59]
	v_mfma_i32_16x16x64_i8 v[44:47], v[148:151], v[192:195], v[44:47]
	v_mfma_i32_16x16x64_i8 v[40:43], v[160:163], v[192:195], v[40:43]
	v_mfma_i32_16x16x64_i8 v[28:31], v[148:151], v[200:203], v[28:31]
	v_mfma_i32_16x16x64_i8 v[24:27], v[160:163], v[200:203], v[24:27]
	v_mfma_i32_16x16x64_i8 v[12:15], v[148:151], v[208:211], v[12:15]
	v_mfma_i32_16x16x64_i8 v[8:11], v[160:163], v[208:211], v[8:11]
	s_setprio 0
	s_setprio 1
	v_mfma_i32_16x16x64_i8 v[52:55], v[164:167], v[180:183], v[52:55]
	v_mfma_i32_16x16x64_i8 v[48:51], v[172:175], v[180:183], v[48:51]
	v_mfma_i32_16x16x64_i8 v[36:39], v[164:167], v[188:191], v[36:39]
	v_mfma_i32_16x16x64_i8 v[32:35], v[172:175], v[188:191], v[32:35]
	v_mfma_i32_16x16x64_i8 v[20:23], v[164:167], v[196:199], v[20:23]
	v_mfma_i32_16x16x64_i8 v[16:19], v[172:175], v[196:199], v[16:19]
	v_mfma_i32_16x16x64_i8 v[4:7], v[164:167], v[204:207], v[4:7]
	v_mfma_i32_16x16x64_i8 v[0:3], v[172:175], v[204:207], v[0:3]
	v_mfma_i32_16x16x64_i8 v[52:55], v[168:171], v[184:187], v[52:55]
	v_mfma_i32_16x16x64_i8 v[48:51], v[176:179], v[184:187], v[48:51]
	v_mfma_i32_16x16x64_i8 v[36:39], v[168:171], v[192:195], v[36:39]
	s_setprio 2
	s_barrier
	v_mfma_i32_16x16x64_i8 v[32:35], v[176:179], v[192:195], v[32:35]
	v_mfma_i32_16x16x64_i8 v[20:23], v[168:171], v[200:203], v[20:23]
	v_mfma_i32_16x16x64_i8 v[16:19], v[176:179], v[200:203], v[16:19]
	v_mfma_i32_16x16x64_i8 v[4:7], v[168:171], v[208:211], v[4:7]
	v_mfma_i32_16x16x64_i8 v[0:3], v[176:179], v[208:211], v[0:3]
	s_setprio 0
	s_add_i32 s80, 0, 0x18000
	s_add_i32 s81, 0, 0x1c000
	v_add_u32_e32 v160, s80, v152
	v_add_u32_e32 v176, s81, v152
	ds_read_b128 v[144:147], v160
	ds_read_b128 v[148:151], v160 offset:1024
	ds_read_b128 v[156:159], v160 offset:2048
	ds_read_b128 v[160:163], v160 offset:3072
	ds_read_b128 v[164:167], v176
	ds_read_b128 v[168:171], v176 offset:1024
	ds_read_b128 v[172:175], v176 offset:2048
	ds_read_b128 v[176:179], v176 offset:3072
	s_add_u32 s58, s58, 0x80000
	s_addc_u32 s59, s59, 0
	s_mov_b32 m0, s53
	v_lshl_add_u64 v[220:221], s[58:59], 0, v[134:135]
	ds_read_b128 v[180:183], v155 offset:32768
	ds_read_b128 v[184:187], v155 offset:33792
	ds_read_b128 v[188:191], v155 offset:34816
	ds_read_b128 v[192:195], v155 offset:35840
	ds_read_b128 v[196:199], v155 offset:36864
	ds_read_b128 v[200:203], v155 offset:37888
	ds_read_b128 v[204:207], v155 offset:38912
	ds_read_b128 v[208:211], v155 offset:39936
	global_load_lds_dwordx4 v[220:221], off
	v_lshl_add_u64 v[220:221], s[58:59], 0, v[130:131]
	s_mov_b32 m0, s60
	s_nop 0
	global_load_lds_dwordx4 v[220:221], off
	s_waitcnt vmcnt(8)
	s_waitcnt lgkmcnt(0)
	s_barrier
	s_setprio 1
	s_waitcnt lgkmcnt(0)
	v_mfma_i32_16x16x64_i8 v[124:127], v[144:147], v[180:183], v[124:127]
	v_mfma_i32_16x16x64_i8 v[120:123], v[156:159], v[180:183], v[120:123]
	v_mfma_i32_16x16x64_i8 v[108:111], v[144:147], v[188:191], v[108:111]
	v_mfma_i32_16x16x64_i8 v[104:107], v[156:159], v[188:191], v[104:107]
	v_mfma_i32_16x16x64_i8 v[92:95], v[144:147], v[196:199], v[92:95]
	v_mfma_i32_16x16x64_i8 v[88:91], v[156:159], v[196:199], v[88:91]
	v_mfma_i32_16x16x64_i8 v[76:79], v[144:147], v[204:207], v[76:79]
	v_mfma_i32_16x16x64_i8 v[72:75], v[156:159], v[204:207], v[72:75]
	v_mfma_i32_16x16x64_i8 v[124:127], v[148:151], v[184:187], v[124:127]
	v_mfma_i32_16x16x64_i8 v[120:123], v[160:163], v[184:187], v[120:123]
	v_mfma_i32_16x16x64_i8 v[108:111], v[148:151], v[192:195], v[108:111]
	v_mfma_i32_16x16x64_i8 v[104:107], v[160:163], v[192:195], v[104:107]
	v_mfma_i32_16x16x64_i8 v[92:95], v[148:151], v[200:203], v[92:95]
	v_mfma_i32_16x16x64_i8 v[88:91], v[160:163], v[200:203], v[88:91]
	v_mfma_i32_16x16x64_i8 v[76:79], v[148:151], v[208:211], v[76:79]
	v_mfma_i32_16x16x64_i8 v[72:75], v[160:163], v[208:211], v[72:75]
	s_setprio 0
	s_setprio 1
	v_mfma_i32_16x16x64_i8 v[116:119], v[164:167], v[180:183], v[116:119]
	v_mfma_i32_16x16x64_i8 v[112:115], v[172:175], v[180:183], v[112:115]
	v_mfma_i32_16x16x64_i8 v[100:103], v[164:167], v[188:191], v[100:103]
	v_mfma_i32_16x16x64_i8 v[96:99], v[172:175], v[188:191], v[96:99]
	v_mfma_i32_16x16x64_i8 v[84:87], v[164:167], v[196:199], v[84:87]
	v_mfma_i32_16x16x64_i8 v[80:83], v[172:175], v[196:199], v[80:83]
	v_mfma_i32_16x16x64_i8 v[68:71], v[164:167], v[204:207], v[68:71]
	v_mfma_i32_16x16x64_i8 v[64:67], v[172:175], v[204:207], v[64:67]
	v_mfma_i32_16x16x64_i8 v[116:119], v[168:171], v[184:187], v[116:119]
	v_mfma_i32_16x16x64_i8 v[112:115], v[176:179], v[184:187], v[112:115]
	v_mfma_i32_16x16x64_i8 v[100:103], v[168:171], v[192:195], v[100:103]
	s_setprio 2
	s_barrier
	v_mfma_i32_16x16x64_i8 v[96:99], v[176:179], v[192:195], v[96:99]
	v_mfma_i32_16x16x64_i8 v[84:87], v[168:171], v[200:203], v[84:87]
	v_mfma_i32_16x16x64_i8 v[80:83], v[176:179], v[200:203], v[80:83]
	v_mfma_i32_16x16x64_i8 v[68:71], v[168:171], v[208:211], v[68:71]
	v_mfma_i32_16x16x64_i8 v[64:67], v[176:179], v[208:211], v[64:67]
	s_setprio 0
	s_add_i32 s58, s80, s34
	v_lshl_add_u64 v[212:213], v[212:213], 0, s[26:27]
	s_mov_b32 m0, s58
	ds_read_b128 v[180:183], v155 offset:49152
	ds_read_b128 v[184:187], v155 offset:50176
	ds_read_b128 v[188:191], v155 offset:51200
	ds_read_b128 v[192:195], v155 offset:52224
	ds_read_b128 v[196:199], v155 offset:53248
	ds_read_b128 v[200:203], v155 offset:54272
	ds_read_b128 v[204:207], v155 offset:55296
	ds_read_b128 v[208:211], v155 offset:56320
	global_load_lds_dwordx4 v[212:213], off
	s_add_i32 m0, s58, 0x2000
	s_add_u32 s56, s56, 0x80080
	v_lshl_add_u64 v[212:213], v[214:215], 0, s[26:27]
	s_addc_u32 s57, s57, 0
	s_add_i32 s58, s81, s34
	global_load_lds_dwordx4 v[212:213], off
	v_lshl_add_u64 v[212:213], s[56:57], 0, v[132:133]
	s_mov_b32 m0, s58
	s_nop 0
	global_load_lds_dwordx4 v[212:213], off
	v_lshl_add_u64 v[212:213], s[56:57], 0, v[128:129]
	s_add_i32 m0, s58, 0x2000
	s_nop 0
	global_load_lds_dwordx4 v[212:213], off
	v_lshl_add_u64 v[212:213], v[216:217], 0, s[26:27]
	s_mov_b32 m0, s63
	s_nop 0
	global_load_lds_dwordx4 v[212:213], off
	v_lshl_add_u64 v[212:213], v[218:219], 0, s[26:27]
	s_mov_b32 m0, s70
	s_nop 0
	global_load_lds_dwordx4 v[212:213], off
	s_waitcnt vmcnt(8)
	s_waitcnt lgkmcnt(0)
	s_barrier
	s_setprio 1
	s_waitcnt lgkmcnt(0)
	v_mfma_i32_16x16x64_i8 v[60:63], v[144:147], v[180:183], v[60:63]
	v_mfma_i32_16x16x64_i8 v[56:59], v[156:159], v[180:183], v[56:59]
	v_mfma_i32_16x16x64_i8 v[44:47], v[144:147], v[188:191], v[44:47]
	v_mfma_i32_16x16x64_i8 v[40:43], v[156:159], v[188:191], v[40:43]
	v_mfma_i32_16x16x64_i8 v[28:31], v[144:147], v[196:199], v[28:31]
	v_mfma_i32_16x16x64_i8 v[24:27], v[156:159], v[196:199], v[24:27]
	v_mfma_i32_16x16x64_i8 v[12:15], v[144:147], v[204:207], v[12:15]
	v_mfma_i32_16x16x64_i8 v[8:11], v[156:159], v[204:207], v[8:11]
	v_mfma_i32_16x16x64_i8 v[60:63], v[148:151], v[184:187], v[60:63]
	v_mfma_i32_16x16x64_i8 v[56:59], v[160:163], v[184:187], v[56:59]
	v_mfma_i32_16x16x64_i8 v[44:47], v[148:151], v[192:195], v[44:47]
	v_mfma_i32_16x16x64_i8 v[40:43], v[160:163], v[192:195], v[40:43]
	v_mfma_i32_16x16x64_i8 v[28:31], v[148:151], v[200:203], v[28:31]
	v_mfma_i32_16x16x64_i8 v[24:27], v[160:163], v[200:203], v[24:27]
	v_mfma_i32_16x16x64_i8 v[12:15], v[148:151], v[208:211], v[12:15]
	v_mfma_i32_16x16x64_i8 v[8:11], v[160:163], v[208:211], v[8:11]
	s_setprio 0
	s_setprio 1
	v_mfma_i32_16x16x64_i8 v[52:55], v[164:167], v[180:183], v[52:55]
	v_mfma_i32_16x16x64_i8 v[48:51], v[172:175], v[180:183], v[48:51]
	v_mfma_i32_16x16x64_i8 v[36:39], v[164:167], v[188:191], v[36:39]
	v_mfma_i32_16x16x64_i8 v[32:35], v[172:175], v[188:191], v[32:35]
	v_mfma_i32_16x16x64_i8 v[20:23], v[164:167], v[196:199], v[20:23]
	v_mfma_i32_16x16x64_i8 v[16:19], v[172:175], v[196:199], v[16:19]
	v_mfma_i32_16x16x64_i8 v[4:7], v[164:167], v[204:207], v[4:7]
	v_mfma_i32_16x16x64_i8 v[0:3], v[172:175], v[204:207], v[0:3]
	v_mfma_i32_16x16x64_i8 v[52:55], v[168:171], v[184:187], v[52:55]
	v_mfma_i32_16x16x64_i8 v[48:51], v[176:179], v[184:187], v[48:51]
	v_mfma_i32_16x16x64_i8 v[36:39], v[168:171], v[192:195], v[36:39]
	s_setprio 2
	s_barrier
	v_mfma_i32_16x16x64_i8 v[32:35], v[176:179], v[192:195], v[32:35]
	v_mfma_i32_16x16x64_i8 v[20:23], v[168:171], v[200:203], v[20:23]
	v_mfma_i32_16x16x64_i8 v[16:19], v[176:179], v[200:203], v[16:19]
	v_mfma_i32_16x16x64_i8 v[4:7], v[168:171], v[208:211], v[4:7]
	v_mfma_i32_16x16x64_i8 v[0:3], v[176:179], v[208:211], v[0:3]
	s_setprio 0
	s_add_i32 s79, s79, 2
	s_add_u32 s54, s54, 0x100
	s_addc_u32 s55, s55, 0
	s_add_u32 s77, s77, 0x100
	s_addc_u32 s78, s78, 0
	s_cmp_gt_u32 s79, 29
	s_cbranch_scc0 .LBB0_771
